# down/out weight conversions riding in layer-0 gate/up phases: software-pipelined per-wave loop (next item's 32 loads issued before current item's LDS transpose and stores)
# speedup vs baseline: 1.0233x; 1.0025x over previous
.LBB0_545:
	v_readlane_b32 s4, v253, 47
	v_readlane_b32 s6, v253, 49
	v_readlane_b32 s5, v253, 48
	s_add_i32 s0, s6, 4
	s_cmp_gt_u32 s0, 12
	v_readlane_b32 s4, v253, 4
	s_cselect_b64 s[0:1], -1, 0
	v_readlane_b32 s5, v253, 5
	s_or_b64 s[0:1], s[4:5], s[0:1]
	s_and_b64 vcc, exec, s[0:1]
	v_readlane_b32 s7, v253, 50
	s_cbranch_vccnz .LBB0_600
	s_cmp_eq_u32 s80, 0
	v_readlane_b32 s4, v253, 43
	s_cselect_b64 s[0:1], -1, 0
	s_cmpk_gt_i32 s4, 0x7f
	s_cselect_b64 s[4:5], -1, 0
	s_and_b64 s[0:1], s[0:1], s[4:5]
	s_andn2_b64 vcc, exec, s[0:1]
	s_cbranch_vccnz .LBB0_562
	v_readlane_b32 s0, v253, 43
	s_lshl_b32 s0, s0, 3
	v_readlane_b32 s4, v253, 45
	s_add_i32 s0, s0, s4
	s_add_i32 s4, s0, 0x1680
	s_cmpk_gt_i32 s4, 0x277f
	v_readlane_b32 s5, v253, 46
	s_cbranch_scc1 .LBB0_562
	v_readlane_b32 s0, v253, 45
	s_mulk_i32 s0, 0x4200
	s_add_i32 s0, s97, s0
	v_readlane_b32 s22, v253, 41
	v_readlane_b32 s23, v253, 42
	v_readlane_b32 s6, v252, 1
	v_readlane_b32 s7, v252, 2
	s_load_dwordx2 s[24:25], s[6:7], 0x58
	s_load_dwordx2 s[26:27], s[6:7], 0xb0
	v_lshlrev_b32_e32 v0, 1, v238
	v_and_b32_e32 v8, 3, v237
	v_and_or_b32 v8, v0, 24, v8
	v_lshrrev_b32_e32 v9, 2, v237
	v_and_or_b32 v8, v9, 4, v8
	v_lshlrev_b32_e32 v8, 2, v8
	v_lshrrev_b32_e32 v7, 5, v238
	v_lshl_add_u32 v2, v7, 12, v8
	v_lshrrev_b32_e32 v12, 3, v238
	v_lshlrev_b32_e32 v11, 3, v238
	v_and_b32_e32 v11, 56, v11
	v_lshlrev_b32_e32 v8, 1, v11
	v_mul_u32_u24_e32 v3, 0x1600, v12
	v_add_u32_e32 v3, v3, v8
	v_lshl_add_u32 v4, v12, 11, v8
	v_and_b32_e32 v9, 31, v237
	v_lshlrev_b32_e32 v9, 2, v9
	v_mul_u32_u24_e32 v10, 0x84, v7
	v_add3_u32 v13, s0, v9, v10
	v_add_u32_e32 v14, 0x400, v13
	v_add_u32_e32 v15, 0x800, v13
	v_add_u32_e32 v16, 0xc00, v13
	v_add_u32_e32 v17, 0x1000, v13
	v_add_u32_e32 v18, 0x1400, v13
	v_add_u32_e32 v19, 0x1800, v13
	v_add_u32_e32 v20, 0x1c00, v13
	v_mul_u32_u24_e32 v9, 0x84, v11
	v_lshlrev_b32_e32 v10, 2, v12
	v_add3_u32 v21, s0, v9, v10
	s_waitcnt lgkmcnt(0)
	s_cmpk_lt_u32 s4, 0x2580
	s_cbranch_scc0 .Lcva_o1
	s_cmpk_gt_u32 s4, 0x1fff
	s_cselect_b32 s5, 1, 0
	s_mul_i32 s6, s5, 0x580
	s_sub_i32 s6, s4, s6
	s_addk_i32 s6, 0xe580
	s_lshr_b32 s7, s6, 5
	s_and_b32 s6, s6, 31
	s_mul_i32 s8, s5, 0xb00000
	s_lshl_b32 s9, s6, 7
	s_add_u32 s8, s8, s9
	s_lshl_b32 s9, s7, 18
	s_add_u32 s8, s8, s9
	s_add_u32 s10, s24, s8
	s_addc_u32 s11, s25, 0
	s_mul_i32 s8, s5, 0x580000
	s_mul_i32 s9, s6, 0x2c000
	s_add_u32 s8, s8, s9
	s_lshl_b32 s9, s7, 7
	s_add_u32 s8, s8, s9
	s_add_u32 s8, s8, 0x2a80000
	s_add_u32 s12, s22, s8
	s_addc_u32 s13, s23, 0
	s_mov_b32 s14, 0xb000
	v_mov_b32_e32 v5, v3
	s_branch .Lcva_d1
.Lcva_o1:
	s_add_i32 s6, s4, 0xffffda80
	s_lshr_b32 s7, s6, 5
	s_and_b32 s6, s6, 31
	s_lshl_b32 s8, s6, 7
	s_lshl_b32 s9, s7, 18
	s_add_u32 s8, s8, s9
	s_add_u32 s10, s26, s8
	s_addc_u32 s11, s27, 0
	s_lshl_b32 s8, s6, 16
	s_lshl_b32 s9, s7, 7
	s_add_u32 s8, s8, s9
	s_add_u32 s8, s8, 0x3580000
	s_add_u32 s12, s22, s8
	s_addc_u32 s13, s23, 0
	s_mov_b32 s14, 0x4000
	v_mov_b32_e32 v5, v4
.Lcva_d1:
	global_load_dword v24, v2, s[10:11] nt
	s_add_u32 s10, s10, 0x2000
	s_addc_u32 s11, s11, 0
	global_load_dword v25, v2, s[10:11] nt
	s_add_u32 s10, s10, 0x2000
	s_addc_u32 s11, s11, 0
	global_load_dword v26, v2, s[10:11] nt
	s_add_u32 s10, s10, 0x2000
	s_addc_u32 s11, s11, 0
	global_load_dword v27, v2, s[10:11] nt
	s_add_u32 s10, s10, 0x2000
	s_addc_u32 s11, s11, 0
	global_load_dword v28, v2, s[10:11] nt
	s_add_u32 s10, s10, 0x2000
	s_addc_u32 s11, s11, 0
	global_load_dword v29, v2, s[10:11] nt
	s_add_u32 s10, s10, 0x2000
	s_addc_u32 s11, s11, 0
	global_load_dword v30, v2, s[10:11] nt
	s_add_u32 s10, s10, 0x2000
	s_addc_u32 s11, s11, 0
	global_load_dword v31, v2, s[10:11] nt
	s_add_u32 s10, s10, 0x2000
	s_addc_u32 s11, s11, 0
	global_load_dword v32, v2, s[10:11] nt
	s_add_u32 s10, s10, 0x2000
	s_addc_u32 s11, s11, 0
	global_load_dword v33, v2, s[10:11] nt
	s_add_u32 s10, s10, 0x2000
	s_addc_u32 s11, s11, 0
	global_load_dword v34, v2, s[10:11] nt
	s_add_u32 s10, s10, 0x2000
	s_addc_u32 s11, s11, 0
	global_load_dword v35, v2, s[10:11] nt
	s_add_u32 s10, s10, 0x2000
	s_addc_u32 s11, s11, 0
	global_load_dword v36, v2, s[10:11] nt
	s_add_u32 s10, s10, 0x2000
	s_addc_u32 s11, s11, 0
	global_load_dword v37, v2, s[10:11] nt
	s_add_u32 s10, s10, 0x2000
	s_addc_u32 s11, s11, 0
	global_load_dword v38, v2, s[10:11] nt
	s_add_u32 s10, s10, 0x2000
	s_addc_u32 s11, s11, 0
	global_load_dword v39, v2, s[10:11] nt
	s_add_u32 s10, s10, 0x2000
	s_addc_u32 s11, s11, 0
	global_load_dword v40, v2, s[10:11] nt
	s_add_u32 s10, s10, 0x2000
	s_addc_u32 s11, s11, 0
	global_load_dword v41, v2, s[10:11] nt
	s_add_u32 s10, s10, 0x2000
	s_addc_u32 s11, s11, 0
	global_load_dword v42, v2, s[10:11] nt
	s_add_u32 s10, s10, 0x2000
	s_addc_u32 s11, s11, 0
	global_load_dword v43, v2, s[10:11] nt
	s_add_u32 s10, s10, 0x2000
	s_addc_u32 s11, s11, 0
	global_load_dword v44, v2, s[10:11] nt
	s_add_u32 s10, s10, 0x2000
	s_addc_u32 s11, s11, 0
	global_load_dword v45, v2, s[10:11] nt
	s_add_u32 s10, s10, 0x2000
	s_addc_u32 s11, s11, 0
	global_load_dword v46, v2, s[10:11] nt
	s_add_u32 s10, s10, 0x2000
	s_addc_u32 s11, s11, 0
	global_load_dword v47, v2, s[10:11] nt
	s_add_u32 s10, s10, 0x2000
	s_addc_u32 s11, s11, 0
	global_load_dword v48, v2, s[10:11] nt
	s_add_u32 s10, s10, 0x2000
	s_addc_u32 s11, s11, 0
	global_load_dword v49, v2, s[10:11] nt
	s_add_u32 s10, s10, 0x2000
	s_addc_u32 s11, s11, 0
	global_load_dword v50, v2, s[10:11] nt
	s_add_u32 s10, s10, 0x2000
	s_addc_u32 s11, s11, 0
	global_load_dword v51, v2, s[10:11] nt
	s_add_u32 s10, s10, 0x2000
	s_addc_u32 s11, s11, 0
	global_load_dword v52, v2, s[10:11] nt
	s_add_u32 s10, s10, 0x2000
	s_addc_u32 s11, s11, 0
	global_load_dword v53, v2, s[10:11] nt
	s_add_u32 s10, s10, 0x2000
	s_addc_u32 s11, s11, 0
	global_load_dword v54, v2, s[10:11] nt
	s_add_u32 s10, s10, 0x2000
	s_addc_u32 s11, s11, 0
	global_load_dword v55, v2, s[10:11] nt
	s_waitcnt vmcnt(0)
.Lcva_top:
	s_mov_b64 s[20:21], s[12:13]
	s_mov_b32 s15, s14
	v_mov_b32_e32 v6, v5
	ds_write2_b32 v13, v24, v25 offset0:0 offset1:66
	ds_write2_b32 v13, v26, v27 offset0:132 offset1:198
	ds_write2_b32 v14, v28, v29 offset0:8 offset1:74
	ds_write2_b32 v14, v30, v31 offset0:140 offset1:206
	ds_write2_b32 v15, v32, v33 offset0:16 offset1:82
	ds_write2_b32 v15, v34, v35 offset0:148 offset1:214
	ds_write2_b32 v16, v36, v37 offset0:24 offset1:90
	ds_write2_b32 v16, v38, v39 offset0:156 offset1:222
	ds_write2_b32 v17, v40, v41 offset0:32 offset1:98
	ds_write2_b32 v17, v42, v43 offset0:164 offset1:230
	ds_write2_b32 v18, v44, v45 offset0:40 offset1:106
	ds_write2_b32 v18, v46, v47 offset0:172 offset1:238
	ds_write2_b32 v19, v48, v49 offset0:48 offset1:114
	ds_write2_b32 v19, v50, v51 offset0:180 offset1:246
	ds_write2_b32 v20, v52, v53 offset0:56 offset1:122
	ds_write2_b32 v20, v54, v55 offset0:188 offset1:254
	s_add_i32 s4, s4, 0x400
	s_cmpk_lt_u32 s4, 0x2780
	s_cbranch_scc0 .Lcva_noload
	s_cmpk_lt_u32 s4, 0x2580
	s_cbranch_scc0 .Lcva_o2
	s_cmpk_gt_u32 s4, 0x1fff
	s_cselect_b32 s5, 1, 0
	s_mul_i32 s6, s5, 0x580
	s_sub_i32 s6, s4, s6
	s_addk_i32 s6, 0xe580
	s_lshr_b32 s7, s6, 5
	s_and_b32 s6, s6, 31
	s_mul_i32 s8, s5, 0xb00000
	s_lshl_b32 s9, s6, 7
	s_add_u32 s8, s8, s9
	s_lshl_b32 s9, s7, 18
	s_add_u32 s8, s8, s9
	s_add_u32 s10, s24, s8
	s_addc_u32 s11, s25, 0
	s_mul_i32 s8, s5, 0x580000
	s_mul_i32 s9, s6, 0x2c000
	s_add_u32 s8, s8, s9
	s_lshl_b32 s9, s7, 7
	s_add_u32 s8, s8, s9
	s_add_u32 s8, s8, 0x2a80000
	s_add_u32 s12, s22, s8
	s_addc_u32 s13, s23, 0
	s_mov_b32 s14, 0xb000
	v_mov_b32_e32 v5, v3
	s_branch .Lcva_d2

.Lcva_d2:
	global_load_dword v24, v2, s[10:11] nt
	s_add_u32 s10, s10, 0x2000
	s_addc_u32 s11, s11, 0
	global_load_dword v25, v2, s[10:11] nt
	s_add_u32 s10, s10, 0x2000
	s_addc_u32 s11, s11, 0
	global_load_dword v26, v2, s[10:11] nt
	s_add_u32 s10, s10, 0x2000
	s_addc_u32 s11, s11, 0
	global_load_dword v27, v2, s[10:11] nt
	s_add_u32 s10, s10, 0x2000
	s_addc_u32 s11, s11, 0
	global_load_dword v28, v2, s[10:11] nt
	s_add_u32 s10, s10, 0x2000
	s_addc_u32 s11, s11, 0
	global_load_dword v29, v2, s[10:11] nt
	s_add_u32 s10, s10, 0x2000
	s_addc_u32 s11, s11, 0
	global_load_dword v30, v2, s[10:11] nt
	s_add_u32 s10, s10, 0x2000
	s_addc_u32 s11, s11, 0
	global_load_dword v31, v2, s[10:11] nt
	s_add_u32 s10, s10, 0x2000
	s_addc_u32 s11, s11, 0
	global_load_dword v32, v2, s[10:11] nt
	s_add_u32 s10, s10, 0x2000
	s_addc_u32 s11, s11, 0
	global_load_dword v33, v2, s[10:11] nt
	s_add_u32 s10, s10, 0x2000
	s_addc_u32 s11, s11, 0
	global_load_dword v34, v2, s[10:11] nt
	s_add_u32 s10, s10, 0x2000
	s_addc_u32 s11, s11, 0
	global_load_dword v35, v2, s[10:11] nt
	s_add_u32 s10, s10, 0x2000
	s_addc_u32 s11, s11, 0
	global_load_dword v36, v2, s[10:11] nt
	s_add_u32 s10, s10, 0x2000
	s_addc_u32 s11, s11, 0
	global_load_dword v37, v2, s[10:11] nt
	s_add_u32 s10, s10, 0x2000
	s_addc_u32 s11, s11, 0
	global_load_dword v38, v2, s[10:11] nt
	s_add_u32 s10, s10, 0x2000
	s_addc_u32 s11, s11, 0
	global_load_dword v39, v2, s[10:11] nt
	s_add_u32 s10, s10, 0x2000
	s_addc_u32 s11, s11, 0
	global_load_dword v40, v2, s[10:11] nt
	s_add_u32 s10, s10, 0x2000
	s_addc_u32 s11, s11, 0
	global_load_dword v41, v2, s[10:11] nt
	s_add_u32 s10, s10, 0x2000
	s_addc_u32 s11, s11, 0
	global_load_dword v42, v2, s[10:11] nt
	s_add_u32 s10, s10, 0x2000
	s_addc_u32 s11, s11, 0
	global_load_dword v43, v2, s[10:11] nt
	s_add_u32 s10, s10, 0x2000
	s_addc_u32 s11, s11, 0
	global_load_dword v44, v2, s[10:11] nt
	s_add_u32 s10, s10, 0x2000
	s_addc_u32 s11, s11, 0
	global_load_dword v45, v2, s[10:11] nt
	s_add_u32 s10, s10, 0x2000
	s_addc_u32 s11, s11, 0
	global_load_dword v46, v2, s[10:11] nt
	s_add_u32 s10, s10, 0x2000
	s_addc_u32 s11, s11, 0
	global_load_dword v47, v2, s[10:11] nt
	s_add_u32 s10, s10, 0x2000
	s_addc_u32 s11, s11, 0
	global_load_dword v48, v2, s[10:11] nt
	s_add_u32 s10, s10, 0x2000
	s_addc_u32 s11, s11, 0
	global_load_dword v49, v2, s[10:11] nt
	s_add_u32 s10, s10, 0x2000
	s_addc_u32 s11, s11, 0
	global_load_dword v50, v2, s[10:11] nt
	s_add_u32 s10, s10, 0x2000
	s_addc_u32 s11, s11, 0
	global_load_dword v51, v2, s[10:11] nt
	s_add_u32 s10, s10, 0x2000
	s_addc_u32 s11, s11, 0
	global_load_dword v52, v2, s[10:11] nt
	s_add_u32 s10, s10, 0x2000
	s_addc_u32 s11, s11, 0
	global_load_dword v53, v2, s[10:11] nt
	s_add_u32 s10, s10, 0x2000
	s_addc_u32 s11, s11, 0
	global_load_dword v54, v2, s[10:11] nt
	s_add_u32 s10, s10, 0x2000
	s_addc_u32 s11, s11, 0
	global_load_dword v55, v2, s[10:11] nt
.Lcva_noload:
	s_waitcnt lgkmcnt(0)
	ds_read2_b32 v[56:57], v21 offset0:0 offset1:8
	ds_read2_b32 v[58:59], v21 offset0:33 offset1:41
	ds_read2_b32 v[60:61], v21 offset0:66 offset1:74
	ds_read2_b32 v[62:63], v21 offset0:99 offset1:107
	ds_read2_b32 v[64:65], v21 offset0:132 offset1:140
	ds_read2_b32 v[66:67], v21 offset0:165 offset1:173
	ds_read2_b32 v[68:69], v21 offset0:198 offset1:206
	ds_read2_b32 v[70:71], v21 offset0:231 offset1:239
	ds_read2_b32 v[72:73], v21 offset0:16 offset1:24
	ds_read2_b32 v[74:75], v21 offset0:49 offset1:57
	ds_read2_b32 v[76:77], v21 offset0:82 offset1:90
	ds_read2_b32 v[78:79], v21 offset0:115 offset1:123
	ds_read2_b32 v[80:81], v21 offset0:148 offset1:156
	ds_read2_b32 v[82:83], v21 offset0:181 offset1:189
	ds_read2_b32 v[84:85], v21 offset0:214 offset1:222
	ds_read2_b32 v[86:87], v21 offset0:247 offset1:255
	s_waitcnt lgkmcnt(8)
	v_cvt_pk_bf16_f32 v88, v56, v58
	v_cvt_pk_bf16_f32 v89, v60, v62
	v_cvt_pk_bf16_f32 v90, v64, v66
	v_cvt_pk_bf16_f32 v91, v68, v70
	v_cvt_pk_bf16_f32 v92, v57, v59
	v_cvt_pk_bf16_f32 v93, v61, v63
	v_cvt_pk_bf16_f32 v94, v65, v67
	v_cvt_pk_bf16_f32 v95, v69, v71
	global_store_dwordx4 v6, v[88:91], s[20:21]
	s_add_u32 s20, s20, s15
	s_addc_u32 s21, s21, 0
	global_store_dwordx4 v6, v[92:95], s[20:21]
	s_add_u32 s20, s20, s15
	s_addc_u32 s21, s21, 0
	s_waitcnt lgkmcnt(0)
	v_cvt_pk_bf16_f32 v96, v72, v74
	v_cvt_pk_bf16_f32 v97, v76, v78
	v_cvt_pk_bf16_f32 v98, v80, v82
	v_cvt_pk_bf16_f32 v99, v84, v86
	v_cvt_pk_bf16_f32 v100, v73, v75
	v_cvt_pk_bf16_f32 v101, v77, v79
	v_cvt_pk_bf16_f32 v102, v81, v83
	v_cvt_pk_bf16_f32 v103, v85, v87
	global_store_dwordx4 v6, v[96:99], s[20:21]
	s_add_u32 s20, s20, s15
	s_addc_u32 s21, s21, 0
	global_store_dwordx4 v6, v[100:103], s[20:21]
	s_cmpk_lt_u32 s4, 0x2780
	s_cbranch_scc0 .Lcva_done
	s_waitcnt vmcnt(4)
	s_branch .Lcva_top
.Lcva_done:
.LBB0_562:
	s_cmp_eq_u32 s80, 2
	v_readlane_b32 s7, v253, 43
	s_cselect_b64 s[0:1], -1, 0
	s_cmp_gt_i32 s7, 63
	s_cselect_b64 s[4:5], -1, 0
	s_and_b64 s[0:1], s[0:1], s[4:5]
	s_andn2_b64 vcc, exec, s[0:1]
	s_cbranch_vccnz .LBB0_584
	s_lshl_b32 s0, s7, 3
	v_readlane_b32 s4, v253, 45
	s_add_i32 s0, s0, s4
	s_add_i32 s6, s0, 0xfffffe00
	s_cmpk_gt_i32 s6, 0x1a7f
	v_readlane_b32 s5, v253, 46
	s_cbranch_scc1 .LBB0_584
	v_readlane_b32 s10, v253, 41
	v_readlane_b32 s0, v253, 45
	v_lshrrev_b32_e32 v2, 2, v237
	v_readlane_b32 s11, v253, 42
	s_add_u32 s7, s10, 0x3780000
	s_mulk_i32 s0, 0x4200
	v_lshlrev_b32_e32 v0, 1, v238
	v_and_b32_e32 v8, 4, v2
	v_and_b32_e32 v2, 3, v237
	s_addc_u32 s8, s11, 0
	s_add_i32 s4, s97, s0
	v_and_or_b32 v9, v0, 24, v2
	v_and_b32_e32 v0, 31, v237
	v_lshl_add_u32 v6, v0, 2, s4
	v_lshlrev_b32_e32 v0, 3, v238
	v_and_b32_e32 v0, 56, v0
	v_readlane_b32 s12, v253, 21
	v_lshlrev_b32_e32 v2, 1, v0
	v_mov_b32_e32 v3, v1
	v_readlane_b32 s20, v253, 25
	v_readlane_b32 s1, v253, 46
	v_readlane_b32 s13, v253, 22
	v_readlane_b32 s14, v253, 23
	v_readlane_b32 s15, v253, 24
	s_add_u32 s0, s12, 0x900000
	v_lshrrev_b32_e32 v11, 3, v238
	v_lshl_add_u64 v[2:3], s[10:11], 0, v[2:3]
	s_mov_b64 s[10:11], 0x4280000
	v_readlane_b32 s22, v253, 27
	v_readlane_b32 s23, v253, 28
	v_readlane_b32 s24, v253, 29
	v_readlane_b32 s25, v253, 30
	v_and_b32_e32 v4, 16, v237
	s_addc_u32 s1, s13, 0
	v_mul_u32_u24_e32 v5, 0x84, v0
	v_lshl_add_u64 v[2:3], v[2:3], 0, s[10:11]
	v_lshlrev_b32_e32 v12, 2, v11
	v_readlane_b32 s26, v253, 31
	v_readlane_b32 s27, v253, 32
	s_mov_b64 s[12:13], s[24:25]
	s_mov_b64 s[10:11], s[22:23]
	v_lshrrev_b32_e32 v10, 5, v238
	v_add3_u32 v12, s4, v5, v12
	v_mov_b32_e32 v5, s13
	v_mov_b32_e32 v16, s11
	v_cmp_eq_u32_e32 vcc, 0, v4
	v_mul_u32_u24_e32 v7, 0x84, v10
	v_mov_b32_e32 v4, s12
	v_cndmask_b32_e32 v5, v5, v16, vcc
	v_mov_b32_e32 v16, s10
	v_or_b32_e32 v13, 8, v11
	v_or_b32_e32 v14, 16, v11
	v_or_b32_e32 v15, 24, v11
	v_cndmask_b32_e32 v4, v4, v16, vcc
	v_lshlrev_b32_e32 v0, 1, v0
	v_add_u32_e32 v16, v6, v7
	v_readlane_b32 s21, v253, 26
	s_mov_b64 s[14:15], s[26:27]
	s_branch .LBB0_566

.LBB0_584:
	s_cmp_eq_u32 s80, 5
	s_cselect_b64 s[0:1], -1, 0
	s_add_i32 s4, s7, 0xffffff80
	s_cmpk_lt_u32 s4, 0x4b
	s_cselect_b64 s[4:5], -1, 0
	s_and_b64 s[0:1], s[0:1], s[4:5]
	s_andn2_b64 vcc, exec, s[0:1]
	s_cbranch_vccnz .LBB0_600
	v_readlane_b32 s0, v253, 43
	s_lshl_b32 s0, s0, 3
	v_readlane_b32 s4, v253, 45
	s_add_i32 s0, s0, s4
	s_addk_i32 s0, 0xfc00
	s_cmpk_gt_i32 s0, 0xcff
	v_readlane_b32 s5, v253, 46
	s_cbranch_scc1 .LBB0_600
	s_add_i32 s4, s0, 0x1a80
	v_readlane_b32 s0, v253, 45
	s_mulk_i32 s0, 0x4200
	s_add_i32 s0, s97, s0
	v_readlane_b32 s22, v253, 41
	v_readlane_b32 s23, v253, 42
	v_readlane_b32 s6, v252, 1
	v_readlane_b32 s7, v252, 2
	s_load_dwordx2 s[24:25], s[6:7], 0x58
	s_load_dwordx2 s[26:27], s[6:7], 0xb0
	v_lshlrev_b32_e32 v0, 1, v238
	v_and_b32_e32 v8, 3, v237
	v_and_or_b32 v8, v0, 24, v8
	v_lshrrev_b32_e32 v9, 2, v237
	v_and_or_b32 v8, v9, 4, v8
	v_lshlrev_b32_e32 v8, 2, v8
	v_lshrrev_b32_e32 v7, 5, v238
	v_lshl_add_u32 v2, v7, 12, v8
	v_lshrrev_b32_e32 v12, 3, v238
	v_lshlrev_b32_e32 v11, 3, v238
	v_and_b32_e32 v11, 56, v11
	v_lshlrev_b32_e32 v8, 1, v11
	v_mul_u32_u24_e32 v3, 0x1600, v12
	v_add_u32_e32 v3, v3, v8
	v_lshl_add_u32 v4, v12, 11, v8
	v_and_b32_e32 v9, 31, v237
	v_lshlrev_b32_e32 v9, 2, v9
	v_mul_u32_u24_e32 v10, 0x84, v7
	v_add3_u32 v13, s0, v9, v10
	v_add_u32_e32 v14, 0x400, v13
	v_add_u32_e32 v15, 0x800, v13
	v_add_u32_e32 v16, 0xc00, v13
	v_add_u32_e32 v17, 0x1000, v13
	v_add_u32_e32 v18, 0x1400, v13
	v_add_u32_e32 v19, 0x1800, v13
	v_add_u32_e32 v20, 0x1c00, v13
	v_mul_u32_u24_e32 v9, 0x84, v11
	v_lshlrev_b32_e32 v10, 2, v12
	v_add3_u32 v21, s0, v9, v10
	s_waitcnt lgkmcnt(0)
	s_cmpk_lt_u32 s4, 0x2580
	s_cbranch_scc0 .Lcvb_o1
	s_cmpk_gt_u32 s4, 0x1fff
	s_cselect_b32 s5, 1, 0
	s_mul_i32 s6, s5, 0x580
	s_sub_i32 s6, s4, s6
	s_addk_i32 s6, 0xe580
	s_lshr_b32 s7, s6, 5
	s_and_b32 s6, s6, 31
	s_mul_i32 s8, s5, 0xb00000
	s_add_u32 s8, s8, 0x1600000
	s_lshl_b32 s9, s6, 7
	s_add_u32 s8, s8, s9
	s_lshl_b32 s9, s7, 18
	s_add_u32 s8, s8, s9
	s_add_u32 s10, s24, s8
	s_addc_u32 s11, s25, 0
	s_mul_i32 s8, s5, 0x580000
	s_mul_i32 s9, s6, 0x2c000
	s_add_u32 s8, s8, s9
	s_lshl_b32 s9, s7, 7
	s_add_u32 s8, s8, s9
	s_add_u32 s8, s8, 0x5200000
	s_add_u32 s12, s22, s8
	s_addc_u32 s13, s23, 0
	s_mov_b32 s14, 0xb000
	v_mov_b32_e32 v5, v3
	s_branch .Lcvb_d1
.Lcvb_o1:
	s_add_i32 s6, s4, 0xffffda80
	s_lshr_b32 s7, s6, 5
	s_and_b32 s6, s6, 31
	s_lshl_b32 s8, s6, 7
	s_lshl_b32 s9, s7, 18
	s_add_u32 s8, s8, s9
	s_add_u32 s8, s8, 0x400000
	s_add_u32 s10, s26, s8
	s_addc_u32 s11, s27, 0
	s_lshl_b32 s8, s6, 16
	s_lshl_b32 s9, s7, 7
	s_add_u32 s8, s8, s9
	s_add_u32 s8, s8, 0x5d00000
	s_add_u32 s12, s22, s8
	s_addc_u32 s13, s23, 0
	s_mov_b32 s14, 0x4000
	v_mov_b32_e32 v5, v4

.Lcvb_top:
	s_mov_b64 s[20:21], s[12:13]
	s_mov_b32 s15, s14
	v_mov_b32_e32 v6, v5
	ds_write2_b32 v13, v24, v25 offset0:0 offset1:66
	ds_write2_b32 v13, v26, v27 offset0:132 offset1:198
	ds_write2_b32 v14, v28, v29 offset0:8 offset1:74
	ds_write2_b32 v14, v30, v31 offset0:140 offset1:206
	ds_write2_b32 v15, v32, v33 offset0:16 offset1:82
	ds_write2_b32 v15, v34, v35 offset0:148 offset1:214
	ds_write2_b32 v16, v36, v37 offset0:24 offset1:90
	ds_write2_b32 v16, v38, v39 offset0:156 offset1:222
	ds_write2_b32 v17, v40, v41 offset0:32 offset1:98
	ds_write2_b32 v17, v42, v43 offset0:164 offset1:230
	ds_write2_b32 v18, v44, v45 offset0:40 offset1:106
	ds_write2_b32 v18, v46, v47 offset0:172 offset1:238
	ds_write2_b32 v19, v48, v49 offset0:48 offset1:114
	ds_write2_b32 v19, v50, v51 offset0:180 offset1:246
	ds_write2_b32 v20, v52, v53 offset0:56 offset1:122
	ds_write2_b32 v20, v54, v55 offset0:188 offset1:254
	s_add_i32 s4, s4, 0x258
	s_cmpk_lt_u32 s4, 0x2780
	s_cbranch_scc0 .Lcvb_noload
	s_cmpk_lt_u32 s4, 0x2580
	s_cbranch_scc0 .Lcvb_o2
	s_cmpk_gt_u32 s4, 0x1fff
	s_cselect_b32 s5, 1, 0
	s_mul_i32 s6, s5, 0x580
	s_sub_i32 s6, s4, s6
	s_addk_i32 s6, 0xe580
	s_lshr_b32 s7, s6, 5
	s_and_b32 s6, s6, 31
	s_mul_i32 s8, s5, 0xb00000
	s_add_u32 s8, s8, 0x1600000
	s_lshl_b32 s9, s6, 7
	s_add_u32 s8, s8, s9
	s_lshl_b32 s9, s7, 18
	s_add_u32 s8, s8, s9
	s_add_u32 s10, s24, s8
	s_addc_u32 s11, s25, 0
	s_mul_i32 s8, s5, 0x580000
	s_mul_i32 s9, s6, 0x2c000
	s_add_u32 s8, s8, s9
	s_lshl_b32 s9, s7, 7
	s_add_u32 s8, s8, s9
	s_add_u32 s8, s8, 0x5200000
	s_add_u32 s12, s22, s8
	s_addc_u32 s13, s23, 0
	s_mov_b32 s14, 0xb000
	v_mov_b32_e32 v5, v3
	s_branch .Lcvb_d2

.Lcvb_done:
.LBB0_600:
	s_mov_b64 s[0:1], 0
